# final RMSNorm on group-local rows: last P6 uses the group barrier too
# baseline (speedup 1.0000x reference)
; #define PG8_WAIT_V(n) asm volatile("s_waitcnt vmcnt(" #n ")" ::: "memory")
; #define PG8_BAR __builtin_amdgcn_s_barrier()
; #define GSYNC() do { for (int r_ = 0; r_ < REP_SYNC; ++r_) xcd_barrier(bar); } while (0)
; template <class Epi, class Sched, bool ALIGN_EPI = false, bool SP2 = false, bool SPLITK = false>
; __device__ __forceinline__ void gemm_phase(PG8_LAS unsigned char* lds, const Gemm g, const Sched& S, const Epi& E) {
;     ...
;     PG8_WAIT_V(0);
;     if constexpr (!ALIGN_EPI) { if (wr == 0) PG8_BAR; }
;     PG8_BAR;
; __global__ void __launch_bounds__(NWAVES * 64, 2) mk_fwd(Args a) {
;     ...
;         GSYNC();
.LBB0_708:
	s_waitcnt vmcnt(0)
	s_barrier
	s_mov_b64 s[16:17], exec
	v_readlane_b32 s12, v253, 36
	v_readlane_b32 s13, v253, 37
	s_and_b64 s[12:13], s[16:17], s[12:13]
	s_mov_b64 exec, s[12:13]
	s_cbranch_execz .LBB0_137
	s_cmp_lg_u32 s98, 0
	s_cbranch_scc0 .Lgb_full_137
	v_readlane_b32 s4, v253, 1
	v_readlane_b32 s12, v253, 56
	v_readlane_b32 s13, v253, 57
	s_add_i32 s99, s99, 4
	s_nop 2
	s_and_b32 s4, s4, 63
	s_lshl_b32 s4, s4, 7
	s_add_i32 s4, s4, 0x3e00
	v_mov_b32_e32 v2, s4
	s_mov_b32 s1, 0
	s_nop 1
	global_atomic_add v2, v234, s[12:13]
	v_mov_b32_e32 v4, 0x5e80
	global_atomic_add v4, v234, s[12:13]

; __device__ __forceinline__ void unpack8(const u32x4 w, f32x4& v0, f32x4& v1) { v0 = (f32x4){bf_lo(w.x), bf_hi(w.x), bf_lo(w.y), bf_hi(w.y)}; v1 = (f32x4){bf_lo(w.z), bf_hi(w.z), bf_lo(w.w), bf_hi(w.w)}; }
; __global__ void __launch_bounds__(NWAVES * 64, 2) mk_fwd(Args a) {
;     ...
;     int tf_ = threadIdx.x; asm volatile("" : "+v"(tf_)); const int lnf = tf_ & 63;
;     for (int m = gw; m < NTOK; m += NGW) {
;         const float rstd = row_rstd(ssqA, m);
; #pragma unroll
;         for (int j = 0; j < 2; ++j) {
;             const int c = 8 * lnf + 512 * j;
;             f32x4 x0, x1; unpack8(*(const v4u*)(XB + (size_t)m * DMOD + c), x0, x1);
;             const f32x4 w0 = *(const f32x4*)(final_norm + c), w1 = *(const f32x4*)(final_norm + c + 4);
;             *(f32x4*)(out + (size_t)m * DMOD + c) = x0 * rstd * w0; *(f32x4*)(out + (size_t)m * DMOD + c + 4) = x1 * rstd * w1;
;         }
;     }
.LBB0_759:
	v_readlane_b32 s0, v253, 52
	v_readlane_b32 s1, v253, 53
	v_readlane_b32 s8, v253, 40
	s_andn2_b64 vcc, exec, s[0:1]
	v_readlane_b32 s10, v253, 42
	v_readlane_b32 s11, v253, 43
	v_readlane_b32 s12, v253, 44
	v_readlane_b32 s13, v253, 45
	v_readlane_b32 s14, v253, 46
	v_readlane_b32 s15, v253, 47
	v_readlane_b32 s16, v255, 2
	v_readlane_b32 s18, v255, 27
	v_readlane_b32 s9, v253, 41
	v_readlane_b32 s17, v255, 3
	v_readlane_b32 s19, v255, 28
	s_movk_i32 s20, 0x4000
	s_cmp_lg_u32 s98, 0
	s_cbranch_scc0 .Lgb_fin_skip
	v_readlane_b32 s2, v253, 1
	v_readlane_b32 s3, v253, 38
	s_nop 3
	s_and_b32 s4, s2, 7
	s_lshl_b32 s4, s4, 3
	s_bfe_u32 s5, s2, 0x30003
	s_add_i32 s4, s4, s5
	s_lshl_b32 s4, s4, 8
	s_lshr_b32 s5, s2, 6
	s_lshl_b32 s5, s5, 6
	s_add_i32 s4, s4, s5
	s_lshl_b32 s3, s3, 3
	s_add_i32 s16, s4, s3
	s_mov_b32 s18, 1
	s_add_i32 s20, s16, 8
	s_andn2_b64 vcc, exec, s[0:1]
.Lgb_fin_skip:
	s_cbranch_vccnz .LBB0_762
	s_ashr_i32 s17, s16, 31
	s_ashr_i32 s19, s18, 31
	v_lshlrev_b32_e32 v0, 5, v244
	s_lshl_b64 s[0:1], s[16:17], 6
	s_lshl_b64 s[2:3], s[18:19], 6
	s_lshl_b64 s[4:5], s[16:17], 12
	v_and_b32_e32 v0, 0x7e0, v0
	v_mov_b32_e32 v1, 0
	v_and_b32_e32 v6, 63, v244
	s_add_u32 s4, s12, s4
	v_lshl_add_u64 v[2:3], s[10:11], 0, v[0:1]
	v_lshlrev_b32_e32 v0, 5, v6
	s_addc_u32 s5, s13, s5
	v_lshl_add_u64 v[4:5], s[4:5], 0, v[0:1]
	s_mov_b64 s[4:5], 0x810
	s_lshl_b64 s[6:7], s[16:17], 11
	v_lshl_add_u64 v[4:5], v[4:5], 0, s[4:5]
	s_lshl_b64 s[4:5], s[18:19], 12
	v_lshl_or_b32 v6, v6, 4, s6
	v_mov_b32_e32 v7, s7
	s_lshl_b64 s[6:7], s[18:19], 11
	v_mov_b32_e32 v0, 0x100000
	v_mov_b32_e32 v8, 0x358637bd
	s_mov_b32 s8, 0x9e00000
.LBB0_761:
	v_lshl_add_u64 v[14:15], s[14:15], 0, v[6:7]
	s_add_u32 s10, s14, s0
	v_add_co_u32_e32 v38, vcc, s8, v14
	s_addc_u32 s11, s15, s1
	s_nop 0
	v_addc_co_u32_e32 v39, vcc, 0, v15, vcc
	global_load_dwordx4 v[10:13], v[2:3], off
	global_load_dwordx4 v[14:17], v[38:39], off
	global_load_dwordx4 v[18:21], v0, s[10:11]
	s_add_u32 s10, s10, 0x100000
	s_addc_u32 s11, s11, 0
	global_load_dwordx4 v[22:25], v1, s[10:11] offset:16
	global_load_dwordx4 v[26:29], v1, s[10:11] offset:32
	global_load_dwordx4 v[30:33], v1, s[10:11] offset:48
	global_load_dwordx4 v[34:37], v[2:3], off offset:16
	s_add_i32 s16, s16, s18
	s_add_u32 s0, s0, s2
	s_addc_u32 s1, s1, s3
	v_lshl_add_u64 v[6:7], v[6:7], 0, s[6:7]
	s_cmp_ge_i32 s16, s20
	s_waitcnt vmcnt(5)
	v_lshlrev_b32_e32 v40, 16, v14
	s_waitcnt vmcnt(3)
	v_pk_add_f32 v[20:21], v[20:21], v[24:25]
	v_pk_add_f32 v[18:19], v[18:19], v[22:23]
	s_waitcnt vmcnt(1)
	v_pk_add_f32 v[22:23], v[28:29], v[32:33]
	v_pk_add_f32 v[24:25], v[26:27], v[30:31]
	v_pk_add_f32 v[20:21], v[20:21], v[22:23]
	v_pk_add_f32 v[18:19], v[18:19], v[24:25]
	v_mov_b32_e32 v23, v20
	v_mov_b32_e32 v22, v19
	v_mov_b32_e32 v19, v21
	v_pk_add_f32 v[18:19], v[22:23], v[18:19]
	v_and_b32_e32 v41, 0xffff0000, v14
	v_add_f32_e32 v9, v18, v19
	v_fmamk_f32 v9, v9, 0x3a800000, v8
	v_rsq_f32_e32 v22, v9
	v_lshlrev_b32_e32 v14, 16, v15
	v_and_b32_e32 v15, 0xffff0000, v15
	v_lshlrev_b32_e32 v42, 16, v16
	v_and_b32_e32 v43, 0xffff0000, v16
	v_lshlrev_b32_e32 v16, 16, v17
	v_and_b32_e32 v17, 0xffff0000, v17
	v_pk_mul_f32 v[18:19], v[22:23], v[40:41] op_sel_hi:[0,1]
	v_pk_mul_f32 v[14:15], v[22:23], v[14:15] op_sel_hi:[0,1]
	v_pk_mul_f32 v[20:21], v[22:23], v[42:43] op_sel_hi:[0,1]
	v_pk_mul_f32 v[16:17], v[22:23], v[16:17] op_sel_hi:[0,1]
	v_pk_mul_f32 v[12:13], v[12:13], v[14:15]
	v_pk_mul_f32 v[10:11], v[10:11], v[18:19]
	s_waitcnt vmcnt(0)
	v_pk_mul_f32 v[16:17], v[36:37], v[16:17]
	v_pk_mul_f32 v[14:15], v[34:35], v[20:21]
	global_store_dwordx4 v[4:5], v[10:13], off offset:-2064
	global_store_dwordx4 v[4:5], v[14:17], off offset:-2048
	global_load_dwordx4 v[10:13], v[38:39], off offset:1024
	s_nop 0
	global_load_dwordx4 v[14:17], v[2:3], off offset:2048
	global_load_dwordx4 v[18:21], v[2:3], off offset:2064
	s_waitcnt vmcnt(2)
	v_lshlrev_b32_e32 v24, 16, v10
	v_and_b32_e32 v25, 0xffff0000, v10
	v_lshlrev_b32_e32 v10, 16, v11
	v_and_b32_e32 v11, 0xffff0000, v11
	v_lshlrev_b32_e32 v26, 16, v12
	v_and_b32_e32 v27, 0xffff0000, v12
	v_lshlrev_b32_e32 v12, 16, v13
	v_and_b32_e32 v13, 0xffff0000, v13
	v_pk_mul_f32 v[24:25], v[22:23], v[24:25] op_sel_hi:[0,1]
	v_pk_mul_f32 v[10:11], v[22:23], v[10:11] op_sel_hi:[0,1]
	v_pk_mul_f32 v[26:27], v[22:23], v[26:27] op_sel_hi:[0,1]
	v_pk_mul_f32 v[22:23], v[22:23], v[12:13] op_sel_hi:[0,1]
	s_waitcnt vmcnt(1)
	v_pk_mul_f32 v[12:13], v[16:17], v[10:11]
	v_pk_mul_f32 v[10:11], v[14:15], v[24:25]
	s_waitcnt vmcnt(0)
	v_pk_mul_f32 v[16:17], v[20:21], v[22:23]
	v_pk_mul_f32 v[14:15], v[18:19], v[26:27]
	global_store_dwordx4 v[4:5], v[10:13], off offset:-16
	global_store_dwordx4 v[4:5], v[14:17], off
	v_lshl_add_u64 v[4:5], v[4:5], 0, s[4:5]
	s_cbranch_scc0 .LBB0_761
